# mod_phase main loop: weight prefetch and LDS reads hoisted with bounded read-ahead (on top of previous version)
# speedup vs baseline: 1.0443x; 1.0009x over previous
; __device__ void mod_phase(const Params& p, float* sm, int w0) {
;     ...
;     const int kg = tid >> 6, col = tid & 63;
;     float acc[33];
; #pragma unroll
;     for (int bi = 0; bi < 33; ++bi) acc[bi] = 0.f;
;     const float* w = p.ada_w + ((long)l * 1024 + kg * 128) * 6144 + e0 + col;
;     for (int d = 0; d < 128; d += 4) {
;       const float w0v = w[(long)d * 6144], w1v = w[(long)(d + 1) * 6144], w2v = w[(long)(d + 2) * 6144], w3v = w[(long)(d + 3) * 6144];
; #pragma unroll
;       for (int bi = 0; bi < 33; ++bi) { const f32x4 sv = *(const f32x4*)(sm + bi * 1024 + kg * 128 + d); acc[bi] += (sv[0] * w0v + sv[1] * w1v) + (sv[2] * w2v + sv[3] * w3v); }
;     }
.LBB0_40:
	s_or_b64 exec, exec, s[0:1]
	s_mul_hi_i32 s0, s2, 0x2aaaaaab
	s_lshr_b32 s1, s0, 31
	s_ashr_i32 s0, s0, 4
	s_add_i32 s10, s0, s1
	s_mul_i32 s0, s10, 0x60
	s_sub_i32 s0, s2, s0
	s_lshl_b32 s0, s0, 6
	s_ashr_i32 s1, s0, 31
	s_mul_i32 s9, s10, 0x1800000
	s_lshl_b64 s[6:7], s[0:1], 2
	s_mul_hi_i32 s8, s10, 0x1800000
	s_add_u32 s6, s9, s6
	s_addc_u32 s7, s8, s7
	v_mov_b32_e32 v53, 0
	v_lshl_add_u64 v[20:21], v[8:9], 0, s[6:7]
	s_mov_b32 s8, -4
	v_mov_b32_e32 v54, v3
	v_mov_b32_e32 v10, 0
	v_mov_b32_e32 v11, v53
	v_mov_b32_e32 v12, 0
	v_mov_b32_e32 v13, v53
	s_waitcnt vmcnt(0)
	v_mov_b32_e32 v14, 0
	v_mov_b32_e32 v15, v53
	v_mov_b32_e32 v16, 0
	v_mov_b32_e32 v17, v53
	v_mov_b32_e32 v18, 0
	v_mov_b32_e32 v19, v53
	v_mov_b32_e32 v22, 0
	v_mov_b32_e32 v23, v53
	v_mov_b32_e32 v24, 0
	v_mov_b32_e32 v25, v53
	v_mov_b32_e32 v26, 0
	v_mov_b32_e32 v27, v53
	v_mov_b32_e32 v28, 0
	v_mov_b32_e32 v29, v53
	v_mov_b32_e32 v30, 0
	v_mov_b32_e32 v31, v53
	v_mov_b32_e32 v32, 0
	v_mov_b32_e32 v33, v53
	v_mov_b32_e32 v34, 0
	v_mov_b32_e32 v35, v53
	v_mov_b32_e32 v36, 0
	v_mov_b32_e32 v37, v53
	v_mov_b32_e32 v38, 0
	v_mov_b32_e32 v39, v53
	v_mov_b32_e32 v40, 0
	v_mov_b32_e32 v41, v53
	v_mov_b32_e32 v42, 0
	v_mov_b32_e32 v43, v53
	s_waitcnt lgkmcnt(0)
	s_barrier
	s_mov_b32 s6, 0xffff4000
	v_add_co_u32_e64 v44, s[6:7], s6, v20
	s_nop 1
	v_addc_co_u32_e64 v45, s[6:7], -1, v21, s[6:7]
	s_movk_i32 s6, 0xa000
	s_nop 0
	v_add_co_u32_e64 v46, s[6:7], s6, v20
	global_load_dword v44, v[44:45], off
	s_nop 0
	v_addc_co_u32_e64 v47, s[6:7], -1, v21, s[6:7]
	v_add_co_u32_e64 v244, s[6:7], s93, v20
	global_load_dword v46, v[46:47], off
	s_nop 0
	global_load_dword v47, v[20:21], off
	v_addc_co_u32_e64 v245, s[6:7], 0, v21, s[6:7]
	global_load_dword v45, v[244:245], off
	v_lshl_add_u64 v[20:21], v[20:21], 0, s[38:39]
.LBB0_41:
	s_waitcnt vmcnt(0)
	v_mov_b32_e32 v240, v44
	v_mov_b32_e32 v241, v45
	v_mov_b32_e32 v242, v46
	v_mov_b32_e32 v243, v47
	v_add_u32_e32 v246, 0xfffe0000, v54
	v_add_u32_e32 v247, 0xffff0000, v54
	v_mov_b32_e32 v248, v54
	ds_read_b128 v[56:59], v246
	ds_read_b128 v[66:69], v246 offset:4096
	ds_read_b128 v[70:73], v246 offset:8192
	ds_read_b128 v[76:79], v246 offset:12288
	ds_read_b128 v[80:83], v246 offset:16384
	ds_read_b128 v[86:89], v246 offset:20480
	ds_read_b128 v[90:93], v246 offset:24576
	ds_read_b128 v[96:99], v246 offset:28672
	ds_read_b128 v[100:103], v246 offset:32768
	ds_read_b128 v[106:109], v246 offset:36864
	ds_read_b128 v[110:113], v246 offset:40960
	ds_read_b128 v[116:119], v246 offset:45056
	ds_read_b128 v[120:123], v246 offset:49152
	s_cmp_lt_i32 s8, 0x78
	s_cbranch_scc0 .Lmod_nopf
	s_mov_b32 s6, 0xffff4000
	v_add_co_u32_e64 v44, s[6:7], s6, v20
	s_nop 1
	v_addc_co_u32_e64 v45, s[6:7], -1, v21, s[6:7]
	s_movk_i32 s6, 0xa000
	s_nop 0
	v_add_co_u32_e64 v46, s[6:7], s6, v20
	global_load_dword v44, v[44:45], off
	s_nop 0
	v_addc_co_u32_e64 v47, s[6:7], -1, v21, s[6:7]
	v_add_co_u32_e64 v244, s[6:7], s93, v20
	global_load_dword v46, v[46:47], off
	s_nop 0
	global_load_dword v47, v[20:21], off
	v_addc_co_u32_e64 v245, s[6:7], 0, v21, s[6:7]
	global_load_dword v45, v[244:245], off
	v_lshl_add_u64 v[20:21], v[20:21], 0, s[38:39]
.Lmod_nopf:
	s_add_i32 s8, s8, 4
	s_cmpk_gt_u32 s8, 0x7b
	s_waitcnt lgkmcnt(12)
	v_mov_b32_e32 v60, v57
	v_mov_b32_e32 v57, v59
	v_mov_b32_e32 v61, v58
	v_pk_mul_f32 v[56:57], v[240:241], v[56:57]
	s_nop 0
	v_pk_fma_f32 v[56:57], v[242:243], v[60:61], v[56:57]
	v_mov_b32_e32 v48, v241
	v_add_f32_e32 v0, v56, v57
	v_add_f32_e32 v53, v53, v0
	ds_read_b128 v[126:129], v246 offset:53248
	ds_read_b128 v[130:133], v246 offset:57344
	s_waitcnt lgkmcnt(12)
	v_mov_b32_e32 v0, v243
	v_mov_b32_e32 v75, v66
	v_mov_b32_e32 v66, v71
	v_mov_b32_e32 v71, v68
	v_mov_b32_e32 v68, v73
	v_mov_b32_e32 v74, v70
	v_pk_mul_f32 v[66:67], v[242:243], v[66:67] op_sel_hi:[0,1]
	v_mov_b32_e32 v70, v72
	v_pk_mul_f32 v[68:69], v[48:49], v[68:69] op_sel_hi:[0,1]
	v_pk_fma_f32 v[66:67], v[240:241], v[74:75], v[66:67] op_sel_hi:[0,1,1]
	v_pk_fma_f32 v[68:69], v[0:1], v[70:71], v[68:69] op_sel_hi:[0,1,1]
	v_pk_add_f32 v[66:67], v[66:67], v[68:69]
	s_nop 0
	v_pk_add_f32 v[42:43], v[42:43], v[66:67]
	ds_read_b128 v[136:139], v246 offset:61440
	ds_read_b128 v[140:143], v247
	s_waitcnt lgkmcnt(12)
	v_mov_b32_e32 v85, v76
	v_mov_b32_e32 v76, v81
	v_mov_b32_e32 v81, v78
	v_mov_b32_e32 v78, v83
	v_mov_b32_e32 v84, v80
	v_pk_mul_f32 v[76:77], v[242:243], v[76:77] op_sel_hi:[0,1]
	v_mov_b32_e32 v80, v82
	v_pk_mul_f32 v[78:79], v[48:49], v[78:79] op_sel_hi:[0,1]
	v_pk_fma_f32 v[76:77], v[240:241], v[84:85], v[76:77] op_sel_hi:[0,1,1]
	v_pk_fma_f32 v[78:79], v[0:1], v[80:81], v[78:79] op_sel_hi:[0,1,1]
	v_pk_add_f32 v[76:77], v[76:77], v[78:79]
	s_nop 0
	v_pk_add_f32 v[40:41], v[40:41], v[76:77]
	ds_read_b128 v[146:149], v247 offset:4096
	ds_read_b128 v[150:153], v247 offset:8192
	s_waitcnt lgkmcnt(12)
	v_mov_b32_e32 v95, v86
	v_mov_b32_e32 v86, v91
	v_mov_b32_e32 v91, v88
	v_mov_b32_e32 v88, v93
	v_mov_b32_e32 v94, v90
	v_pk_mul_f32 v[86:87], v[242:243], v[86:87] op_sel_hi:[0,1]
	v_mov_b32_e32 v90, v92
	v_pk_mul_f32 v[88:89], v[48:49], v[88:89] op_sel_hi:[0,1]
	v_pk_fma_f32 v[86:87], v[240:241], v[94:95], v[86:87] op_sel_hi:[0,1,1]
	v_pk_fma_f32 v[88:89], v[0:1], v[90:91], v[88:89] op_sel_hi:[0,1,1]
	v_pk_add_f32 v[86:87], v[86:87], v[88:89]
	s_nop 0
	v_pk_add_f32 v[38:39], v[38:39], v[86:87]
	ds_read_b128 v[156:159], v247 offset:12288
	ds_read_b128 v[160:163], v247 offset:16384
	s_waitcnt lgkmcnt(12)
; __device__ void mod_phase(const Params& p, float* sm, int w0) {
;     ...
;     for (int d = 0; d < 128; d += 4) {
;       const float w0v = w[(long)d * 6144], w1v = w[(long)(d + 1) * 6144], w2v = w[(long)(d + 2) * 6144], w3v = w[(long)(d + 3) * 6144];
; #pragma unroll
;       for (int bi = 0; bi < 33; ++bi) { const f32x4 sv = *(const f32x4*)(sm + bi * 1024 + kg * 128 + d); acc[bi] += (sv[0] * w0v + sv[1] * w1v) + (sv[2] * w2v + sv[3] * w3v); }
;     }
	v_mov_b32_e32 v105, v96
	v_mov_b32_e32 v96, v101
	v_mov_b32_e32 v101, v98
	v_mov_b32_e32 v98, v103
	v_mov_b32_e32 v104, v100
	v_pk_mul_f32 v[96:97], v[242:243], v[96:97] op_sel_hi:[0,1]
	v_mov_b32_e32 v100, v102
	v_pk_mul_f32 v[98:99], v[48:49], v[98:99] op_sel_hi:[0,1]
	v_pk_fma_f32 v[96:97], v[240:241], v[104:105], v[96:97] op_sel_hi:[0,1,1]
	v_pk_fma_f32 v[98:99], v[0:1], v[100:101], v[98:99] op_sel_hi:[0,1,1]
	v_pk_add_f32 v[96:97], v[96:97], v[98:99]
	s_nop 0
	v_pk_add_f32 v[36:37], v[36:37], v[96:97]
	ds_read_b128 v[166:169], v247 offset:20480
	ds_read_b128 v[170:173], v247 offset:24576
	s_waitcnt lgkmcnt(12)
	v_mov_b32_e32 v115, v106
	v_mov_b32_e32 v106, v111
	v_mov_b32_e32 v111, v108
	v_mov_b32_e32 v108, v113
	v_mov_b32_e32 v114, v110
	v_pk_mul_f32 v[106:107], v[242:243], v[106:107] op_sel_hi:[0,1]
	v_mov_b32_e32 v110, v112
	v_pk_mul_f32 v[108:109], v[48:49], v[108:109] op_sel_hi:[0,1]
	v_pk_fma_f32 v[106:107], v[240:241], v[114:115], v[106:107] op_sel_hi:[0,1,1]
	v_pk_fma_f32 v[108:109], v[0:1], v[110:111], v[108:109] op_sel_hi:[0,1,1]
	v_pk_add_f32 v[106:107], v[106:107], v[108:109]
	s_nop 0
	v_pk_add_f32 v[34:35], v[34:35], v[106:107]
	ds_read_b128 v[176:179], v247 offset:28672
	ds_read_b128 v[180:183], v247 offset:32768
	s_waitcnt lgkmcnt(12)
	v_mov_b32_e32 v125, v116
	v_mov_b32_e32 v116, v121
	v_mov_b32_e32 v121, v118
	v_mov_b32_e32 v118, v123
	v_mov_b32_e32 v124, v120
	v_pk_mul_f32 v[116:117], v[242:243], v[116:117] op_sel_hi:[0,1]
	v_mov_b32_e32 v120, v122
	v_pk_mul_f32 v[118:119], v[48:49], v[118:119] op_sel_hi:[0,1]
	v_pk_fma_f32 v[116:117], v[240:241], v[124:125], v[116:117] op_sel_hi:[0,1,1]
	v_pk_fma_f32 v[118:119], v[0:1], v[120:121], v[118:119] op_sel_hi:[0,1,1]
	v_pk_add_f32 v[116:117], v[116:117], v[118:119]
	s_nop 0
	v_pk_add_f32 v[32:33], v[32:33], v[116:117]
	ds_read_b128 v[186:189], v247 offset:36864
	ds_read_b128 v[190:193], v247 offset:40960
	s_waitcnt lgkmcnt(12)
	v_mov_b32_e32 v135, v126
	v_mov_b32_e32 v126, v131
	v_mov_b32_e32 v131, v128
	v_mov_b32_e32 v128, v133
	v_mov_b32_e32 v134, v130
	v_pk_mul_f32 v[126:127], v[242:243], v[126:127] op_sel_hi:[0,1]
	v_mov_b32_e32 v130, v132
	v_pk_mul_f32 v[128:129], v[48:49], v[128:129] op_sel_hi:[0,1]
	v_pk_fma_f32 v[126:127], v[240:241], v[134:135], v[126:127] op_sel_hi:[0,1,1]
	v_pk_fma_f32 v[128:129], v[0:1], v[130:131], v[128:129] op_sel_hi:[0,1,1]
	v_pk_add_f32 v[126:127], v[126:127], v[128:129]
	s_nop 0
	v_pk_add_f32 v[30:31], v[30:31], v[126:127]
	ds_read_b128 v[196:199], v247 offset:45056
	ds_read_b128 v[200:203], v247 offset:49152
	s_waitcnt lgkmcnt(12)
	v_mov_b32_e32 v145, v136
	v_mov_b32_e32 v136, v141
	v_mov_b32_e32 v141, v138
	v_mov_b32_e32 v138, v143
	v_mov_b32_e32 v144, v140
	v_pk_mul_f32 v[136:137], v[242:243], v[136:137] op_sel_hi:[0,1]
	v_mov_b32_e32 v140, v142
	v_pk_mul_f32 v[138:139], v[48:49], v[138:139] op_sel_hi:[0,1]
	v_pk_fma_f32 v[136:137], v[240:241], v[144:145], v[136:137] op_sel_hi:[0,1,1]
	v_pk_fma_f32 v[138:139], v[0:1], v[140:141], v[138:139] op_sel_hi:[0,1,1]
	v_pk_add_f32 v[136:137], v[136:137], v[138:139]
	s_nop 0
	v_pk_add_f32 v[28:29], v[28:29], v[136:137]
	ds_read_b128 v[206:209], v247 offset:53248
	ds_read_b128 v[210:213], v247 offset:57344
	s_waitcnt lgkmcnt(12)
	v_mov_b32_e32 v155, v146
	v_mov_b32_e32 v146, v151
	v_mov_b32_e32 v151, v148
	v_mov_b32_e32 v148, v153
	v_mov_b32_e32 v154, v150
	v_pk_mul_f32 v[146:147], v[242:243], v[146:147] op_sel_hi:[0,1]
	v_mov_b32_e32 v150, v152
	v_pk_mul_f32 v[148:149], v[48:49], v[148:149] op_sel_hi:[0,1]
	v_pk_fma_f32 v[146:147], v[240:241], v[154:155], v[146:147] op_sel_hi:[0,1,1]
	v_pk_fma_f32 v[148:149], v[0:1], v[150:151], v[148:149] op_sel_hi:[0,1,1]
	v_pk_add_f32 v[146:147], v[146:147], v[148:149]
	s_nop 0
	v_pk_add_f32 v[26:27], v[26:27], v[146:147]
	ds_read_b128 v[216:219], v247 offset:61440
	ds_read_b128 v[220:223], v248
	s_waitcnt lgkmcnt(12)
	v_mov_b32_e32 v165, v156
	v_mov_b32_e32 v156, v161
	v_mov_b32_e32 v161, v158
	v_mov_b32_e32 v158, v163
	v_mov_b32_e32 v164, v160
	v_pk_mul_f32 v[156:157], v[242:243], v[156:157] op_sel_hi:[0,1]
	v_mov_b32_e32 v160, v162
	v_pk_mul_f32 v[158:159], v[48:49], v[158:159] op_sel_hi:[0,1]
	v_pk_fma_f32 v[156:157], v[240:241], v[164:165], v[156:157] op_sel_hi:[0,1,1]
	v_pk_fma_f32 v[158:159], v[0:1], v[160:161], v[158:159] op_sel_hi:[0,1,1]
	v_pk_add_f32 v[156:157], v[156:157], v[158:159]
	s_nop 0
	v_pk_add_f32 v[24:25], v[24:25], v[156:157]
	s_waitcnt lgkmcnt(10)
	v_mov_b32_e32 v175, v166
	v_mov_b32_e32 v166, v171
	v_mov_b32_e32 v171, v168
	v_mov_b32_e32 v168, v173
	v_mov_b32_e32 v174, v170
	v_pk_mul_f32 v[166:167], v[242:243], v[166:167] op_sel_hi:[0,1]
	v_mov_b32_e32 v170, v172
	v_pk_mul_f32 v[168:169], v[48:49], v[168:169] op_sel_hi:[0,1]
	v_pk_fma_f32 v[166:167], v[240:241], v[174:175], v[166:167] op_sel_hi:[0,1,1]
	v_pk_fma_f32 v[168:169], v[0:1], v[170:171], v[168:169] op_sel_hi:[0,1,1]
	v_pk_add_f32 v[166:167], v[166:167], v[168:169]
	s_nop 0
	v_pk_add_f32 v[22:23], v[22:23], v[166:167]
	s_waitcnt lgkmcnt(8)
; __device__ void mod_phase(const Params& p, float* sm, int w0) {
;     ...
;     for (int d = 0; d < 128; d += 4) {
;       const float w0v = w[(long)d * 6144], w1v = w[(long)(d + 1) * 6144], w2v = w[(long)(d + 2) * 6144], w3v = w[(long)(d + 3) * 6144];
; #pragma unroll
;       for (int bi = 0; bi < 33; ++bi) { const f32x4 sv = *(const f32x4*)(sm + bi * 1024 + kg * 128 + d); acc[bi] += (sv[0] * w0v + sv[1] * w1v) + (sv[2] * w2v + sv[3] * w3v); }
;     }
;     __syncthreads();
; #pragma unroll
;     for (int bi = 0; bi < 33; ++bi) sm[(kg * 33 + bi) * 64 + col] = acc[bi];
;     __syncthreads();
;     for (int i = tid; i < 33 * 64; i += NTHREADS) {
;       const int bi = i >> 6, cc = i & 63; float s = p.ada_b[l * 6144 + e0 + cc];
; #pragma unroll
;       for (int k = 0; k < 8; ++k) s += sm[(k * 33 + bi) * 64 + cc];
;       p.mod[((long)l * 33 + bi) * 6144 + e0 + cc] = s;
	v_mov_b32_e32 v185, v176
	v_mov_b32_e32 v176, v181
	v_mov_b32_e32 v181, v178
	v_mov_b32_e32 v178, v183
	v_mov_b32_e32 v184, v180
	v_pk_mul_f32 v[176:177], v[242:243], v[176:177] op_sel_hi:[0,1]
	v_mov_b32_e32 v180, v182
	v_pk_mul_f32 v[178:179], v[48:49], v[178:179] op_sel_hi:[0,1]
	v_pk_fma_f32 v[176:177], v[240:241], v[184:185], v[176:177] op_sel_hi:[0,1,1]
	v_pk_fma_f32 v[178:179], v[0:1], v[180:181], v[178:179] op_sel_hi:[0,1,1]
	v_pk_add_f32 v[176:177], v[176:177], v[178:179]
	s_nop 0
	v_pk_add_f32 v[18:19], v[18:19], v[176:177]
	s_waitcnt lgkmcnt(6)
	v_mov_b32_e32 v195, v186
	v_mov_b32_e32 v186, v191
	v_mov_b32_e32 v191, v188
	v_mov_b32_e32 v188, v193
	v_mov_b32_e32 v194, v190
	v_pk_mul_f32 v[186:187], v[242:243], v[186:187] op_sel_hi:[0,1]
	v_mov_b32_e32 v190, v192
	v_pk_mul_f32 v[188:189], v[48:49], v[188:189] op_sel_hi:[0,1]
	v_pk_fma_f32 v[186:187], v[240:241], v[194:195], v[186:187] op_sel_hi:[0,1,1]
	v_pk_fma_f32 v[188:189], v[0:1], v[190:191], v[188:189] op_sel_hi:[0,1,1]
	v_pk_add_f32 v[186:187], v[186:187], v[188:189]
	s_nop 0
	v_pk_add_f32 v[16:17], v[16:17], v[186:187]
	s_waitcnt lgkmcnt(4)
	v_mov_b32_e32 v205, v196
	v_mov_b32_e32 v196, v201
	v_mov_b32_e32 v201, v198
	v_mov_b32_e32 v198, v203
	v_mov_b32_e32 v204, v200
	v_pk_mul_f32 v[196:197], v[242:243], v[196:197] op_sel_hi:[0,1]
	v_mov_b32_e32 v200, v202
	v_pk_mul_f32 v[198:199], v[48:49], v[198:199] op_sel_hi:[0,1]
	v_pk_fma_f32 v[196:197], v[240:241], v[204:205], v[196:197] op_sel_hi:[0,1,1]
	v_pk_fma_f32 v[198:199], v[0:1], v[200:201], v[198:199] op_sel_hi:[0,1,1]
	v_pk_add_f32 v[196:197], v[196:197], v[198:199]
	s_nop 0
	v_pk_add_f32 v[14:15], v[14:15], v[196:197]
	s_waitcnt lgkmcnt(2)
	v_mov_b32_e32 v215, v206
	v_mov_b32_e32 v206, v211
	v_mov_b32_e32 v211, v208
	v_mov_b32_e32 v208, v213
	v_mov_b32_e32 v214, v210
	v_pk_mul_f32 v[206:207], v[242:243], v[206:207] op_sel_hi:[0,1]
	v_mov_b32_e32 v210, v212
	v_pk_mul_f32 v[208:209], v[48:49], v[208:209] op_sel_hi:[0,1]
	v_pk_fma_f32 v[206:207], v[240:241], v[214:215], v[206:207] op_sel_hi:[0,1,1]
	v_pk_fma_f32 v[208:209], v[0:1], v[210:211], v[208:209] op_sel_hi:[0,1,1]
	v_pk_add_f32 v[206:207], v[206:207], v[208:209]
	s_nop 0
	v_pk_add_f32 v[12:13], v[12:13], v[206:207]
	s_waitcnt lgkmcnt(0)
	v_mov_b32_e32 v225, v216
	v_mov_b32_e32 v216, v221
	v_mov_b32_e32 v224, v220
	v_pk_mul_f32 v[242:243], v[242:243], v[216:217] op_sel_hi:[0,1]
	v_pk_fma_f32 v[240:241], v[240:241], v[224:225], v[242:243] op_sel_hi:[0,1,1]
	v_mov_b32_e32 v243, v218
	v_mov_b32_e32 v218, v223
	v_mov_b32_e32 v242, v222
	v_pk_mul_f32 v[216:217], v[48:49], v[218:219] op_sel_hi:[0,1]
	v_pk_fma_f32 v[242:243], v[0:1], v[242:243], v[216:217] op_sel_hi:[0,1,1]
	v_pk_add_f32 v[240:241], v[240:241], v[242:243]
	s_nop 0
	v_pk_add_f32 v[10:11], v[10:11], v[240:241]
	v_add_u32_e32 v54, 16, v54
	s_cbranch_scc0 .LBB0_41
	s_barrier
	ds_write2st64_b32 v52, v53, v43 offset1:1
	ds_write2st64_b32 v52, v42, v41 offset0:2 offset1:3
	ds_write2st64_b32 v52, v40, v39 offset0:4 offset1:5
	ds_write2st64_b32 v52, v38, v37 offset0:6 offset1:7
	ds_write2st64_b32 v52, v36, v35 offset0:8 offset1:9
	ds_write2st64_b32 v52, v34, v33 offset0:10 offset1:11
	ds_write2st64_b32 v52, v32, v31 offset0:12 offset1:13
	ds_write2st64_b32 v52, v30, v29 offset0:14 offset1:15
	ds_write2st64_b32 v52, v28, v27 offset0:16 offset1:17
	ds_write2st64_b32 v52, v26, v25 offset0:18 offset1:19
	ds_write2st64_b32 v52, v24, v23 offset0:20 offset1:21
	ds_write2st64_b32 v52, v22, v19 offset0:22 offset1:23
	ds_write2st64_b32 v52, v18, v17 offset0:24 offset1:25
	ds_write2st64_b32 v52, v16, v15 offset0:26 offset1:27
	ds_write2st64_b32 v52, v14, v13 offset0:28 offset1:29
	ds_write2st64_b32 v52, v12, v11 offset0:30 offset1:31
	ds_write_b32 v52, v10 offset:8192
	s_waitcnt lgkmcnt(0)
	s_barrier
	s_and_saveexec_b64 s[8:9], s[4:5]
	s_cbranch_execz .LBB0_36
	s_mul_i32 s6, s10, 0x1800
	s_add_i32 s6, s6, s0
	v_or_b32_e32 v10, s6, v49
	v_readlane_b32 s12, v252, 49
	v_ashrrev_i32_e32 v11, 31, v10
	v_readlane_b32 s22, v252, 59
	v_readlane_b32 s23, v252, 60
	s_mul_hi_i32 s11, s10, 33
	s_mul_i32 s10, s10, 33
	v_lshl_add_u64 v[10:11], v[10:11], 2, s[22:23]
	v_lshl_add_u64 v[12:13], s[0:1], 2, v[4:5]
	s_mov_b64 s[0:1], 0
	v_mov_b32_e32 v0, v2
	v_readlane_b32 s13, v252, 50
	v_readlane_b32 s14, v252, 51
	v_readlane_b32 s15, v252, 52
	v_readlane_b32 s16, v252, 53
	v_readlane_b32 s17, v252, 54
	v_readlane_b32 s18, v252, 55
	v_readlane_b32 s19, v252, 56
	v_readlane_b32 s20, v252, 57
	v_readlane_b32 s21, v252, 58
	v_readlane_b32 s24, v252, 61
	v_readlane_b32 s25, v252, 62
	v_readlane_b32 s26, v252, 63
	v_readlane_b32 s27, v253, 0
